# MLA attention: first LDS-spilled q fragment kept in unused VGPRs v248-251 (one LDS re-read and one exposed wait less per tile)
# speedup vs baseline: 1.0086x; 1.0086x over previous
; __device__ __forceinline__ int v_st(int k, int c) { const int kk = (k & ~0xC) | ((k & 4) << 1) | ((k & 8) >> 1); return ((kk >> 3) * 4 + (c >> 5)) * 512 + ((kk & 7) * 32 + (c & 31)) * 2; }
; __device__ __forceinline__ int v_rd_base(int lane) { return ((lane & 3) << 3) | (((lane >> 2) & 3) << 6) | (((lane >> 4) & 1) << 5) | (((lane >> 5) & 1) << 8); }
; #define SWRITE(b, i) do { *(bf16x8*)(V_lds + (b) * SHM_V + vst0) = sr_[i].vs0; *(bf16x8*)(V_lds + (b) * SHM_V + vst1) = sr_[i].vs1; \
;     *(bf16x8*)(K_lds + (b) * SHM_K + kdst0) = sr_[i].ks0; *(bf16x8*)(K_lds + (b) * SHM_K + kdst0 + 32 * KW * 2) = sr_[i].ks1; \
;     if constexpr (KW == 192) *(bf16x8*)(K_lds + (b) * SHM_K + kdst2) = sr_[i].ks2; } while (0)
; #define VM0() asm volatile("s_waitcnt vmcnt(0)" ::: "memory")
; #define WGBAR() asm volatile("s_waitcnt lgkmcnt(0)\n\ts_barrier" ::: "memory")
; template <int DQK, int KW, bool DIFF, int SDEPTH, int QSP, int NBUF>
; __device__ __forceinline__ void attn_unit(const UnitP& P, char* lds) {
;     ...
;   { const bf16_t* Qp = P.Qw + (long)r32 * P.ldq + hi * 8;
; #pragma unroll
;     for (int d0 = 0; d0 < NQR; ++d0) qr[d0] = *reinterpret_cast<const bf16x8*>(Qp + d0 * 16);
; #pragma unroll
;     for (int d0 = NQR; d0 < DQK / 16; ++d0) *reinterpret_cast<bf16x8*>(qsp + (d0 - NQR) * 1024) = *reinterpret_cast<const bf16x8*>(Qp + d0 * 16); }
;   const int sr = tid >> 4, sc = (tid & 15) * 8, vst0 = v_st(sr, sc), vst1 = v_st(32 + sr, sc);
;   const int vb0 = (int)(uintptr_t)V_lds + v_rd_base(lane);
;   int kb[4];
; #pragma unroll
;   for (int q = 0; q < 4; ++q) kb[q] = coffB + kswz<KW>(r32, q * 32 + hi * 16);
;   const unsigned voff = (unsigned)(sr * P.ldv + sc) * 2u, koff = (unsigned)(sr * P.ldk0 + sc) * 2u, koff2 = (unsigned)((tid >> 3) * P.ldk1 + (tid & 7) * 8) * 2u;
;   const int kdst0 = kswz<KW>(sr, sc * 2), kdst2 = kswz<KW>(tid >> 3, 256 + (tid & 7) * 16);
;   struct { bf16x8 vs0, vs1, ks0, ks1, ks2; } sr_[SDEPTH];
;     ...
;     SLOAD(0, 0); VM0(); SWRITE(0, 0); SLOAD(0, 1); WGBAR();
.LBB0_50:
	s_ashr_i32 s35, s2, 4
	s_and_b32 s2, s2, 15
	s_add_u32 s8, s8, s27
	s_mul_i32 s11, s35, 0x900
	s_addc_u32 s9, s9, s28
	s_mul_hi_i32 s10, s35, 0x900
	s_add_u32 s42, s8, s11
	s_addc_u32 s43, s9, s10
	s_add_u32 s8, s11, s6
	s_addc_u32 s9, s10, s7
	s_mul_i32 s7, s43, 0x1800
	s_mul_hi_u32 s10, s42, 0x1800
	s_add_i32 s10, s10, s7
	s_mul_i32 s7, s42, 0x1800
	s_add_u32 s7, s14, s7
	s_waitcnt vmcnt(0)
	v_mov_b32_e32 v6, v184
	s_addc_u32 s11, s15, s10
	s_mul_i32 s10, s2, 0x180
	s_add_u32 s10, s7, s10
	v_and_b32_e32 v192, 31, v6
	v_mul_u32_u24_e32 v0, 0xc00, v192
	s_addc_u32 s11, s11, 0
	v_lshlrev_b32_e32 v0, 1, v0
	s_lshl_b64 s[12:13], s[8:9], 12
	v_lshl_add_u64 v[2:3], s[10:11], 0, v[0:1]
	s_add_u32 s10, s16, s12
	s_addc_u32 s11, s17, s13
	s_lshl_b32 s30, s2, 7
	s_lshl_b32 s7, s2, 8
	v_bfe_u32 v193, v6, 5, 1
	s_add_u32 s10, s10, s7
	v_lshlrev_b32_e32 v170, 4, v193
	v_mov_b32_e32 v171, v1
	s_addc_u32 s11, s11, 0
	s_lshl_b64 s[8:9], s[8:9], 7
	v_lshl_add_u64 v[36:37], v[2:3], 0, v[170:171]
	s_add_u32 s8, s23, s8
	global_load_dwordx4 v[2:5], v[36:37], off offset:288
	global_load_dwordx4 v[8:11], v[36:37], off offset:320
	global_load_dwordx4 v[12:15], v[36:37], off offset:352
	s_addc_u32 s9, s24, s9
	s_add_u32 s2, s19, s12
	v_lshlrev_b32_e32 v38, 3, v6
	s_addc_u32 s13, s20, s13
	v_and_b32_e32 v0, 0x78, v38
	s_add_u32 s12, s2, s7
	v_ashrrev_i32_e32 v7, 4, v6
	v_lshlrev_b32_e32 v0, 1, v0
	s_addc_u32 s13, s13, 0
	v_lshl_or_b32 v78, v7, 12, v0
	v_mov_b32_e32 v79, v1
	v_lshl_add_u64 v[84:85], s[12:13], 0, v[78:79]
	v_add_co_u32_e32 v20, vcc, s87, v84
	v_lshlrev_b32_e32 v16, 4, v6
	s_nop 0
	v_addc_co_u32_e32 v21, vcc, 0, v85, vcc
	v_lshl_add_u64 v[82:83], s[10:11], 0, v[78:79]
	v_and_b32_e32 v74, 0x70, v16
	v_ashrrev_i32_e32 v39, 3, v6
	v_add_co_u32_e32 v28, vcc, s87, v82
	global_load_dwordx4 v[16:19], v78, s[12:13]
	global_load_dwordx4 v[24:27], v78, s[10:11]
	v_addc_co_u32_e32 v29, vcc, 0, v83, vcc
	global_load_dwordx4 v[20:23], v[20:21], off
	v_lshl_or_b32 v80, v39, 7, v74
	global_load_dwordx4 v[28:31], v[28:29], off
	v_ashrrev_i32_e32 v194, 6, v6
	global_load_dwordx4 v[32:35], v80, s[8:9]
	global_load_dwordx4 v[130:133], v[36:37], off
	global_load_dwordx4 v[126:129], v[36:37], off offset:32
	global_load_dwordx4 v[122:125], v[36:37], off offset:64
	global_load_dwordx4 v[118:121], v[36:37], off offset:96
	global_load_dwordx4 v[114:117], v[36:37], off offset:128
	global_load_dwordx4 v[110:113], v[36:37], off offset:160
	global_load_dwordx4 v[106:109], v[36:37], off offset:192
	global_load_dwordx4 v[102:105], v[36:37], off offset:224
	global_load_dwordx4 v[98:101], v[36:37], off offset:256
	s_movk_i32 s2, 0xc00
	v_and_b32_e32 v171, 63, v6
	v_mul_lo_u32 v40, v194, s2
	s_add_i32 s2, 0, 0x1e800
	v_lshlrev_b32_e32 v94, 4, v171
	v_add_u32_e32 v36, s2, v40
	v_add_u32_e32 v197, v36, v94
	v_and_b32_e32 v41, 0xfffff0, v7
	v_lshlrev_b32_e32 v42, 1, v7
	v_and_or_b32 v41, v42, 8, v41
	v_lshrrev_b32_e32 v43, 1, v7
	v_mov_b32_e32 v81, v1
	v_lshl_add_u64 v[86:87], s[8:9], 0, v[80:81]
	s_movk_i32 s2, 0x2000
	v_mul_u32_u24_e32 v75, 0x180, v192
	v_bitop3_b32 v200, v170, v75, v74 bitop3:0xde
	s_add_i32 s8, 0, 0x1e000
	s_cmp_lg_u32 0, -1
	s_mov_b32 s48, 0
	s_cselect_b32 s9, 0, 0
	s_mov_b32 s49, s48
	s_mov_b32 s50, s48
	s_mov_b32 s51, s48
	s_waitcnt vmcnt(16)
	ds_write_b128 v197, v[2:5]
	v_mov_b64_e32 v[248:249], v[2:3]
	v_mov_b64_e32 v[250:251], v[4:5]
	s_waitcnt vmcnt(15)
	ds_write_b128 v197, v[8:11] offset:1024
	s_waitcnt vmcnt(14)
	ds_write_b128 v197, v[12:15] offset:2048
	v_add_u32_e32 v5, 32, v7
	v_and_b32_e32 v8, 0xfffff0, v5
	v_lshlrev_b32_e32 v5, 1, v5
	v_and_or_b32 v5, v5, 8, v8
	v_lshrrev_b32_e32 v2, 1, v41
	v_bfe_u32 v3, v38, 5, 2
	v_and_b32_e32 v4, 3, v7
	v_lshrrev_b32_e32 v5, 1, v5
	v_or_b32_e32 v2, v2, v3
	v_and_or_b32 v4, v43, 4, v4
	v_or_b32_e32 v3, v5, v3
	v_lshlrev_b32_e32 v2, 9, v2
	v_lshlrev_b32_e32 v4, 6, v4
	v_lshlrev_b32_e32 v3, 9, v3
	v_and_b32_e32 v5, 48, v0
	v_or3_b32 v201, v2, v4, v5
	v_or3_b32 v202, v3, v4, v5
	v_mul_lo_u32 v2, v7, s83
	v_and_b32_e32 v3, 0x70, v6
	v_lshlrev_b32_e32 v4, 4, v39
	v_xad_u32 v203, v0, v3, v2
	v_or_b32_e32 v2, 0x100, v74
	v_mul_lo_u32 v3, v39, s83
	v_and_b32_e32 v4, 0x70, v4
	v_xad_u32 v204, v4, v2, v3
	v_add_u32_e32 v88, 0, v201
	v_add_u32_e32 v89, 0, v202
	v_add_u32_e32 v2, 0, v203
	s_waitcnt vmcnt(0)
	s_waitcnt vmcnt(13)
	ds_write_b128 v88, v[16:19]
	s_waitcnt vmcnt(11)
	ds_write_b128 v89, v[20:23]
	ds_write_b128 v2, v[24:27] offset:49152
	s_waitcnt vmcnt(10)
	ds_write_b128 v2, v[28:31] offset:61440
	v_add_u32_e32 v2, 0, v204
	s_waitcnt vmcnt(9)
	ds_write_b128 v2, v[32:35] offset:49152
	v_add_co_u32_e32 v2, vcc, s91, v84
	v_add_u32_e32 v7, 0, v200
	s_nop 0
	v_addc_co_u32_e32 v3, vcc, 0, v85, vcc
	global_load_dwordx4 v[50:53], v[2:3], off
	v_add_co_u32_e32 v2, vcc, s75, v84
	v_or_b32_e32 v8, 32, v170
	s_nop 0
	v_addc_co_u32_e32 v3, vcc, 0, v85, vcc
	global_load_dwordx4 v[54:57], v[2:3], off
	v_add_co_u32_e32 v2, vcc, s91, v82
	v_bitop3_b32 v207, v8, v75, v74 bitop3:0xde
	s_nop 0
	v_addc_co_u32_e32 v3, vcc, 0, v83, vcc
	global_load_dwordx4 v[58:61], v[2:3], off
	v_add_co_u32_e32 v2, vcc, s75, v82
	v_add_u32_e32 v76, 0, v207
	s_nop 0
	v_addc_co_u32_e32 v3, vcc, 0, v83, vcc
	global_load_dwordx4 v[62:65], v[2:3], off
	v_add_co_u32_e32 v2, vcc, s2, v86
	s_mov_b32 s52, s48
	s_nop 0
	v_addc_co_u32_e32 v3, vcc, 0, v87, vcc
	global_load_dwordx4 v[66:69], v[2:3], off
	s_waitcnt lgkmcnt(0)
	s_barrier
; #define SWRITE(b, i) do { *(bf16x8*)(V_lds + (b) * SHM_V + vst0) = sr_[i].vs0; *(bf16x8*)(V_lds + (b) * SHM_V + vst1) = sr_[i].vs1; \
;     *(bf16x8*)(K_lds + (b) * SHM_K + kdst0) = sr_[i].ks0; *(bf16x8*)(K_lds + (b) * SHM_K + kdst0 + 32 * KW * 2) = sr_[i].ks1; \
;     if constexpr (KW == 192) *(bf16x8*)(K_lds + (b) * SHM_K + kdst2) = sr_[i].ks2; } while (0)
; #define PSM(X0, X1, MN, AL, FIRST) do { if constexpr (DIFF) partialSM_ps<FIRST>(X0, X1, m_reg, AL, negm); else partialSM<DQK>(X0, X1, m_reg, MN, AL); } while (0)
; #define VM0() asm volatile("s_waitcnt vmcnt(0)" ::: "memory")
; #define WGBAR() asm volatile("s_waitcnt lgkmcnt(0)\n\ts_barrier" ::: "memory")
; template <int DQK> __device__ __forceinline__ void partialSM(f32x16& p0, f32x16& p1, float& m_reg, float& mn, float& alpha) {
;   constexpr float SCALE = Sc<DQK>::SCALE; constexpr float C = SCALE * 1.4426950408889634f;
;   float pmax = p0[0];
; #pragma unroll
;   for (int r = 1; r < 16; ++r) pmax = fmaxf(pmax, p0[r]);
; #pragma unroll
;   for (int r = 0; r < 16; ++r) pmax = fmaxf(pmax, p1[r]);
;   { auto rr = __builtin_amdgcn_permlane32_swap(__float_as_uint(pmax), __float_as_uint(pmax), false, false);
;     pmax = fmaxf(__uint_as_float(rr[0]), __uint_as_float(rr[1])); }
;   if (__builtin_expect(__all(pmax - m_reg <= THR / SCALE), 1)) { mn = m_reg; alpha = 1.f; }
;   else { mn = fmaxf(m_reg, pmax); alpha = __builtin_amdgcn_exp2f((m_reg - mn) * C); m_reg = mn; }
;   float mnC = -mn * C;
; #pragma unroll
;   for (int r = 0; r < 16; ++r) p0[r] = fmaf(p0[r], C, mnC);
; #pragma unroll
;   for (int r = 0; r < 16; ++r) p1[r] = fmaf(p1[r], C, mnC);
; #pragma unroll
;   for (int r = 0; r < 16; ++r) p0[r] = __builtin_amdgcn_exp2f(p0[r]);
; template <int DQK, int KW, bool DIFF, int SDEPTH, int QSP, int NBUF>
; __device__ __forceinline__ void attn_unit(const UnitP& P, char* lds) {
;     ...
;     qkt<DQK, KW, QSP>(pA0, pA1, K_lds, kb, qr, qsp, negm); PSM(pA0, pA1, mnA, alA, true);
;     VM0(); SWRITE(1, 0); if (2 < NT) SLOAD(0, 2); WGBAR();
	ds_read_b128 v[2:5], v7 offset:49152
	ds_read_b128 v[8:11], v76 offset:49152
	ds_read_b128 v[12:15], v76 offset:61440
	ds_read_b128 v[16:19], v7 offset:61440
	s_waitcnt vmcnt(13) lgkmcnt(3)
	v_mfma_f32_32x32x16_bf16 v[34:49], v[2:5], v[130:133], 0
	v_or_b32_e32 v2, 64, v170
	v_bitop3_b32 v205, v2, v75, v74 bitop3:0xde
	s_mov_b32 s53, s48
	s_mov_b32 s54, s48
	s_mov_b32 s55, s48
	s_mov_b32 s56, s48
	s_mov_b32 s57, s48
	s_waitcnt lgkmcnt(0)
	v_mfma_f32_32x32x16_bf16 v[18:33], v[16:19], v[130:133], 0
	v_add_u32_e32 v16, 0, v205
	ds_read_b128 v[2:5], v16 offset:49152
	ds_read_b128 v[70:73], v16 offset:61440
	s_mov_b32 s58, s48
	s_mov_b32 s59, s48
	s_mov_b32 s60, s48
	s_mov_b32 s61, s48
	s_mov_b32 s62, s48
	s_waitcnt vmcnt(12)
	v_mfma_f32_32x32x16_bf16 v[34:49], v[8:11], v[126:129], v[34:49]
	v_or_b32_e32 v8, 0x60, v170
	v_bitop3_b32 v206, v8, v75, v74 bitop3:0xde
	v_add_u32_e32 v17, 0, v206
	s_mov_b32 s63, s48
	s_mul_i32 s10, s35, 0x48000
	s_mov_b32 s2, 2
	v_cmp_gt_u32_e64 s[38:39], 32, v171
	v_mfma_f32_32x32x16_bf16 v[18:33], v[12:15], v[126:129], v[18:33]
	ds_read_b128 v[8:11], v17 offset:49152
	ds_read_b128 v[12:15], v17 offset:61440
	v_mov_b32_e32 v199, 0
	s_waitcnt vmcnt(11) lgkmcnt(3)
	v_mfma_f32_32x32x16_bf16 v[34:49], v[2:5], v[122:125], v[34:49]
	s_waitcnt lgkmcnt(2)
	v_mfma_f32_32x32x16_bf16 v[18:33], v[70:73], v[122:125], v[18:33]
	ds_read_b128 v[2:5], v7 offset:49280
	ds_read_b128 v[70:73], v7 offset:61568
	s_waitcnt vmcnt(10) lgkmcnt(3)
	v_mfma_f32_32x32x16_bf16 v[34:49], v[8:11], v[118:121], v[34:49]
	s_waitcnt lgkmcnt(2)
	v_mfma_f32_32x32x16_bf16 v[18:33], v[12:15], v[118:121], v[18:33]
	ds_read_b128 v[8:11], v76 offset:49280
	ds_read_b128 v[12:15], v76 offset:61568
	s_waitcnt vmcnt(9) lgkmcnt(3)
	v_mfma_f32_32x32x16_bf16 v[34:49], v[2:5], v[114:117], v[34:49]
	s_waitcnt lgkmcnt(2)
	v_mfma_f32_32x32x16_bf16 v[18:33], v[70:73], v[114:117], v[18:33]
	ds_read_b128 v[2:5], v16 offset:49280
	ds_read_b128 v[70:73], v16 offset:61568
	s_waitcnt vmcnt(8) lgkmcnt(3)
	v_mfma_f32_32x32x16_bf16 v[34:49], v[8:11], v[110:113], v[34:49]
	s_waitcnt lgkmcnt(2)
	v_mfma_f32_32x32x16_bf16 v[18:33], v[12:15], v[110:113], v[18:33]
	ds_read_b128 v[8:11], v17 offset:49280
	ds_read_b128 v[12:15], v17 offset:61568
	s_waitcnt vmcnt(7) lgkmcnt(3)
	v_mfma_f32_32x32x16_bf16 v[34:49], v[2:5], v[106:109], v[34:49]
	s_waitcnt lgkmcnt(2)
	v_mfma_f32_32x32x16_bf16 v[18:33], v[70:73], v[106:109], v[18:33]
	ds_read_b128 v[2:5], v7 offset:49408
	ds_read_b128 v[70:73], v7 offset:61696
	v_and_b32_e32 v7, 0x3fffffc0, v6
	v_lshl_add_u32 v195, v7, 2, s8
	v_lshlrev_b32_e32 v7, 3, v171
	v_lshlrev_b32_e32 v6, 1, v6
	v_and_b32_e32 v6, 32, v6
	s_mov_b32 s8, 1
	s_waitcnt vmcnt(6) lgkmcnt(3)
	v_mfma_f32_32x32x16_bf16 v[34:49], v[8:11], v[102:105], v[34:49]
	v_lshl_add_u32 v198, v192, 2, v195
	s_waitcnt lgkmcnt(2)
	v_mfma_f32_32x32x16_bf16 v[18:33], v[12:15], v[102:105], v[18:33]
	ds_read_b128 v[8:11], v76 offset:49408
	ds_read_b128 v[12:15], v76 offset:61696
	s_waitcnt vmcnt(5) lgkmcnt(3)
	v_mfma_f32_32x32x16_bf16 v[34:49], v[2:5], v[98:101], v[34:49]
	s_waitcnt lgkmcnt(2)
	v_mfma_f32_32x32x16_bf16 v[18:33], v[70:73], v[98:101], v[18:33]
	ds_read_b128 v[74:77], v16 offset:49408
	ds_read_b128 v[90:93], v16 offset:61696
	ds_read_b128 v[2:5], v197
	s_waitcnt lgkmcnt(0)
	v_mfma_f32_32x32x16_bf16 v[34:49], v[8:11], v[2:5], v[34:49]
	v_and_b32_e32 v8, 0xc0, v94
	v_and_or_b32 v16, v7, 24, v8
	v_and_b32_e32 v7, 0x100, v7
	v_or3_b32 v6, v16, v6, v7
	v_add_u32_e32 v196, s9, v6
	v_mfma_f32_32x32x16_bf16 v[18:33], v[12:15], v[2:5], v[18:33]
	ds_read_b128 v[2:5], v17 offset:49408
	ds_read_b128 v[70:73], v17 offset:61696
	ds_read_b128 v[8:11], v197 offset:1024
	s_waitcnt lgkmcnt(0)
	v_mfma_f32_32x32x16_bf16 v[34:49], v[74:77], v[8:11], v[34:49]
	v_mfma_f32_32x32x16_bf16 v[18:33], v[90:93], v[8:11], v[18:33]
	ds_read_b128 v[74:77], v197 offset:2048
	s_waitcnt vmcnt(0)
	s_waitcnt lgkmcnt(0)
	v_mfma_f32_32x32x16_bf16 v[34:49], v[2:5], v[74:77], v[34:49]
	v_mov_b64_e32 v[2:3], s[48:49]
	v_mov_b64_e32 v[4:5], s[50:51]
	v_mov_b64_e32 v[6:7], s[52:53]
	v_mov_b64_e32 v[8:9], s[54:55]
	v_mov_b64_e32 v[10:11], s[56:57]
	v_mov_b64_e32 v[12:13], s[58:59]
	v_mov_b64_e32 v[14:15], s[60:61]
	v_mfma_f32_32x32x16_bf16 v[18:33], v[70:73], v[74:77], v[18:33]
	s_nop 3
	v_max_f32_e32 v70, v35, v35
	v_max_f32_e32 v71, v34, v34
	v_max_f32_e32 v70, v71, v70
	v_max3_f32 v70, v70, v36, v37
	v_max3_f32 v70, v70, v38, v39
	v_max3_f32 v70, v70, v40, v41
	v_max3_f32 v70, v70, v42, v43
	v_max3_f32 v70, v70, v44, v45
	v_max3_f32 v70, v70, v46, v47
	v_max3_f32 v70, v70, v48, v49
	v_max3_f32 v70, v70, v18, v19
	v_max3_f32 v70, v70, v20, v21
	v_max3_f32 v70, v70, v22, v23
	v_max3_f32 v70, v70, v24, v25
	v_max3_f32 v70, v70, v26, v27
	v_max3_f32 v70, v70, v28, v29
	v_max3_f32 v70, v70, v30, v31
	v_max3_f32 v70, v70, v32, v33
	v_mov_b32_e32 v71, v70
	s_nop 1
	v_permlane32_swap_b32_e32 v70, v71
	v_mov_b64_e32 v[16:17], s[62:63]
	v_max_f32_e32 v71, v71, v71
	v_max_f32_e32 v70, v70, v70
	s_mov_b32 s51, 0x80000
	v_max_f32_e32 v72, v70, v71
	v_add_co_u32_e32 v70, vcc, s51, v84
	s_mov_b32 s52, 0xa0000
	s_nop 0
	v_addc_co_u32_e32 v71, vcc, 0, v85, vcc
	global_load_dwordx4 v[134:137], v[70:71], off
	v_add_co_u32_e32 v70, vcc, s52, v84
	s_movk_i32 s53, 0x4000
	s_nop 0
	v_addc_co_u32_e32 v71, vcc, 0, v85, vcc
	global_load_dwordx4 v[138:141], v[70:71], off
	v_add_co_u32_e32 v70, vcc, s51, v82
	v_add_f32_e32 v73, 0x7149f2ca, v72
	s_nop 0
	v_addc_co_u32_e32 v71, vcc, 0, v83, vcc
	global_load_dwordx4 v[142:145], v[70:71], off
	v_add_co_u32_e32 v70, vcc, s52, v82
	s_mov_b32 s49, 0x42ddb3d8
	s_nop 0
	v_addc_co_u32_e32 v71, vcc, 0, v83, vcc
	global_load_dwordx4 v[146:149], v[70:71], off
	v_add_co_u32_e32 v70, vcc, s53, v86
	v_readlane_b32 s56, v255, 9
	s_nop 0
	v_addc_co_u32_e32 v71, vcc, 0, v87, vcc
	global_load_dwordx4 v[150:153], v[70:71], off
	v_max_f32_e32 v70, 0xf149f2ca, v72
	v_sub_f32_e32 v71, 0xf149f2ca, v70
	v_cmp_ge_f32_e32 vcc, s49, v73
	v_mul_f32_e32 v71, 0x3dd53b94, v71
	v_exp_f32_e32 v71, v71
	s_cmp_eq_u64 vcc, exec
	s_cselect_b64 vcc, -1, 0
	v_cndmask_b32_e32 v209, v70, v185, vcc
	v_mul_f32_e32 v70, 0xbdd53b94, v209
	v_cndmask_b32_e64 v208, v71, 1.0, vcc
	v_mov_b32_e32 v71, v70
	v_fmac_f32_e32 v71, 0x3dd53b94, v49
	s_add_i32 s9, 0, 0x12000
	v_pk_fma_f32 v[182:183], v[18:19], s[86:87], v[70:71] op_sel_hi:[1,0,0]
	v_add_u32_e32 v18, s9, v203
	s_lshl_b32 s11, s6, 7
	v_fmamk_f32 v34, v34, 0x3dd53b94, v70
	v_fmamk_f32 v35, v35, 0x3dd53b94, v70
	v_fmamk_f32 v36, v36, 0x3dd53b94, v70
	v_fmamk_f32 v37, v37, 0x3dd53b94, v70
	v_fmamk_f32 v38, v38, 0x3dd53b94, v70
	v_fmamk_f32 v39, v39, 0x3dd53b94, v70
	v_fmamk_f32 v40, v40, 0x3dd53b94, v70
	v_fmamk_f32 v41, v41, 0x3dd53b94, v70
	v_fmamk_f32 v42, v42, 0x3dd53b94, v70
	v_fmamk_f32 v43, v43, 0x3dd53b94, v70
	v_fmamk_f32 v44, v44, 0x3dd53b94, v70
	v_fmamk_f32 v45, v45, 0x3dd53b94, v70
	v_fmamk_f32 v46, v46, 0x3dd53b94, v70
	v_fmamk_f32 v47, v47, 0x3dd53b94, v70
	v_fmamk_f32 v48, v48, 0x3dd53b94, v70
	s_waitcnt vmcnt(9)
; template <int DQK, int KW, int QSP> __device__ __forceinline__ void qkt(f32x16& p0, f32x16& p1, const char* Ks, const int (&kb)[4], const bf16x8* qr, const char* qsp, const f32x16& cinit) {
;   p0 = cinit; p1 = cinit;
;   constexpr int N = DQK / 16;
;     ...
;   bf16x8 f0[2], f1[2];
;   f0[0] = KRD(0, 1); f1[0] = KRD(0, 0);
; #pragma unroll
;   for (int d0 = 0; d0 < N; ++d0) {
;     if (d0 + 1 < N) { f0[(d0 + 1) & 1] = KRD(d0 + 1, 1); f1[(d0 + 1) & 1] = KRD(d0 + 1, 0); }
;     __builtin_amdgcn_sched_barrier(0x406);
;     bf16x8 qf;
;     if constexpr (QSP > 0) { if (d0 >= N - QSP) qf = *reinterpret_cast<const bf16x8*>(qsp + (d0 - (N - QSP)) * 1024); else qf = qr[d0]; } else qf = qr[d0];
;     p0 = __builtin_amdgcn_mfma_f32_32x32x16_bf16(f0[d0 & 1], qf, p0, 0, 0, 0);
;     p1 = __builtin_amdgcn_mfma_f32_32x32x16_bf16(f1[d0 & 1], qf, p1, 0, 0, 0);
;     __builtin_amdgcn_sched_barrier(0x406); }
	ds_write_b128 v88, v[50:53] offset:16384
	s_waitcnt vmcnt(8)
	ds_write_b128 v89, v[54:57] offset:16384
	s_waitcnt vmcnt(7)
	ds_write_b128 v18, v[58:61]
	s_waitcnt vmcnt(6)
	ds_write_b128 v18, v[62:65] offset:12288
	v_add_u32_e32 v18, s9, v204
	s_mul_hi_i32 s9, s35, 0x48000
	s_add_u32 s10, s10, s11
	v_exp_f32_e32 v226, v34
	v_exp_f32_e32 v228, v35
	v_exp_f32_e32 v224, v36
	v_exp_f32_e32 v227, v37
	v_exp_f32_e32 v221, v38
	v_exp_f32_e32 v225, v39
	v_exp_f32_e32 v220, v40
	v_exp_f32_e32 v222, v41
	v_exp_f32_e32 v217, v42
	v_exp_f32_e32 v219, v43
	v_exp_f32_e32 v215, v44
	v_exp_f32_e32 v218, v45
	v_exp_f32_e32 v213, v46
	v_exp_f32_e32 v216, v47
	v_exp_f32_e32 v212, v48
	v_exp_f32_e32 v214, v71
	s_waitcnt vmcnt(5)
	ds_write_b128 v18, v[66:69]
	s_addc_u32 s11, s9, 0
	s_mul_hi_i32 s9, s35, 0x900000
	s_mul_i32 s35, s35, 0x900000
	s_lshl_b32 s6, s6, 12
	s_waitcnt lgkmcnt(0)
	s_barrier
	s_add_u32 s6, s35, s6
	v_pk_fma_f32 v[162:163], v[32:33], s[86:87], v[70:71] op_sel_hi:[1,0,0]
	v_pk_fma_f32 v[164:165], v[30:31], s[86:87], v[70:71] op_sel_hi:[1,0,0]
	v_pk_fma_f32 v[166:167], v[28:29], s[86:87], v[70:71] op_sel_hi:[1,0,0]
	v_pk_fma_f32 v[168:169], v[26:27], s[86:87], v[70:71] op_sel_hi:[1,0,0]
	v_pk_fma_f32 v[176:177], v[24:25], s[86:87], v[70:71] op_sel_hi:[1,0,0]
	v_pk_fma_f32 v[178:179], v[22:23], s[86:87], v[70:71] op_sel_hi:[1,0,0]
	v_pk_fma_f32 v[180:181], v[20:21], s[86:87], v[70:71] op_sel_hi:[1,0,0]
	v_lshl_add_u64 v[172:173], s[10:11], 0, v[80:81]
	s_addc_u32 s11, s9, 0
	s_or_b32 s10, s6, s7
	v_mov_b64_e32 v[64:65], v[16:17]
	v_mov_b64_e32 v[48:49], v[16:17]
	v_mov_b64_e32 v[32:33], v[16:17]
	v_lshl_add_u64 v[174:175], s[10:11], 0, v[78:79]
	v_mov_b64_e32 v[62:63], v[14:15]
	v_mov_b64_e32 v[60:61], v[12:13]
	v_mov_b64_e32 v[58:59], v[10:11]
	v_mov_b64_e32 v[56:57], v[8:9]
	v_mov_b64_e32 v[54:55], v[6:7]
	v_mov_b64_e32 v[52:53], v[4:5]
	v_mov_b64_e32 v[50:51], v[2:3]
	v_mov_b64_e32 v[46:47], v[14:15]
	v_mov_b64_e32 v[44:45], v[12:13]
	v_mov_b64_e32 v[42:43], v[10:11]
	v_mov_b64_e32 v[40:41], v[8:9]
	v_mov_b64_e32 v[38:39], v[6:7]
	v_mov_b64_e32 v[36:37], v[4:5]
	v_mov_b64_e32 v[34:35], v[2:3]
	v_mov_b64_e32 v[30:31], v[14:15]
	v_mov_b64_e32 v[28:29], v[12:13]
	v_mov_b64_e32 v[26:27], v[10:11]
	v_mov_b64_e32 v[24:25], v[8:9]
	v_mov_b64_e32 v[22:23], v[6:7]
	v_mov_b64_e32 v[20:21], v[4:5]
	v_mov_b64_e32 v[18:19], v[2:3]
	s_mov_b32 s54, 0xf800000
	v_readlane_b32 s57, v255, 10
.LBB0_51:
	s_mul_i32 s6, s8, 0x6000
	s_add_i32 s6, s6, 0
	v_add_u32_e32 v210, s6, v207
	v_add_u32_e32 v211, s6, v200
	ds_read_b128 v[154:157], v210 offset:49152
	ds_read_b128 v[158:161], v210 offset:61440
	ds_read_b128 v[66:69], v211 offset:61440
	ds_read_b128 v[70:73], v211 offset:49152
	v_add_u32_e32 v223, s6, v205
	v_add_u32_e32 v229, s6, v206
	s_waitcnt lgkmcnt(0)
	v_mfma_f32_32x32x16_bf16 v[82:97], v[70:73], v[130:133], 0
	v_exp_f32_e32 v182, v182
	v_exp_f32_e32 v183, v183
	v_exp_f32_e32 v180, v180
	v_exp_f32_e32 v181, v181
	v_exp_f32_e32 v178, v178
	v_exp_f32_e32 v179, v179
	v_exp_f32_e32 v176, v176
	v_mfma_f32_32x32x16_bf16 v[66:81], v[66:69], v[130:133], 0
	ds_read_b128 v[230:233], v223 offset:49152
	ds_read_b128 v[234:237], v223 offset:61440
	v_exp_f32_e32 v177, v177
	v_exp_f32_e32 v168, v168
	v_exp_f32_e32 v169, v169
	v_exp_f32_e32 v167, v167
	v_mfma_f32_32x32x16_bf16 v[66:81], v[158:161], v[126:129], v[66:81]
	v_mfma_f32_32x32x16_bf16 v[82:97], v[154:157], v[126:129], v[82:97]
	ds_read_b128 v[154:157], v229 offset:49152
	ds_read_b128 v[158:161], v229 offset:61440
	s_waitcnt lgkmcnt(2)
	v_mfma_f32_32x32x16_bf16 v[66:81], v[234:237], v[122:125], v[66:81]
	v_mfma_f32_32x32x16_bf16 v[82:97], v[230:233], v[122:125], v[82:97]
	ds_read_b128 v[230:233], v211 offset:49280
	ds_read_b128 v[234:237], v211 offset:61568
	s_waitcnt lgkmcnt(2)
	v_mfma_f32_32x32x16_bf16 v[66:81], v[158:161], v[118:121], v[66:81]
	v_mfma_f32_32x32x16_bf16 v[82:97], v[154:157], v[118:121], v[82:97]
	ds_read_b128 v[154:157], v210 offset:49280
	ds_read_b128 v[158:161], v210 offset:61568
	s_waitcnt lgkmcnt(2)
	v_mfma_f32_32x32x16_bf16 v[66:81], v[234:237], v[114:117], v[66:81]
	v_mfma_f32_32x32x16_bf16 v[82:97], v[230:233], v[114:117], v[82:97]
	ds_read_b128 v[230:233], v223 offset:49280
	ds_read_b128 v[234:237], v223 offset:61568
	s_waitcnt lgkmcnt(2)
	v_mfma_f32_32x32x16_bf16 v[66:81], v[158:161], v[110:113], v[66:81]
	v_mfma_f32_32x32x16_bf16 v[82:97], v[154:157], v[110:113], v[82:97]
	ds_read_b128 v[154:157], v229 offset:49280
	ds_read_b128 v[158:161], v229 offset:61568
	s_waitcnt lgkmcnt(2)
	v_mfma_f32_32x32x16_bf16 v[66:81], v[234:237], v[106:109], v[66:81]
	v_mfma_f32_32x32x16_bf16 v[82:97], v[230:233], v[106:109], v[82:97]
	ds_read_b128 v[230:233], v211 offset:49408
	ds_read_b128 v[234:237], v211 offset:61696
	s_waitcnt lgkmcnt(2)
	v_mfma_f32_32x32x16_bf16 v[66:81], v[158:161], v[102:105], v[66:81]
	v_mfma_f32_32x32x16_bf16 v[82:97], v[154:157], v[102:105], v[82:97]
	ds_read_b128 v[154:157], v210 offset:49408
	ds_read_b128 v[158:161], v210 offset:61696
	s_waitcnt lgkmcnt(2)
	v_mfma_f32_32x32x16_bf16 v[66:81], v[234:237], v[98:101], v[66:81]
	v_mfma_f32_32x32x16_bf16 v[82:97], v[230:233], v[98:101], v[82:97]
	ds_read_b128 v[230:233], v223 offset:49408
	ds_read_b128 v[234:237], v223 offset:61696
	v_exp_f32_e32 v223, v166
	s_waitcnt lgkmcnt(2)
	v_mfma_f32_32x32x16_bf16 v[66:81], v[158:161], v[248:251], v[66:81]
	v_mfma_f32_32x32x16_bf16 v[82:97], v[154:157], v[248:251], v[82:97]
	ds_read_b128 v[158:161], v229 offset:49408
	ds_read_b128 v[154:157], v229 offset:61696
	ds_read_b128 v[238:241], v197 offset:1024
	v_exp_f32_e32 v229, v164
	s_waitcnt lgkmcnt(0)
; __device__ __forceinline__ void finishSM(f32x16& p0, f32x16& p1, float alpha, float& l_reg, bf16x8& pa0, bf16x8& pa1, bf16x8& pa2, bf16x8& pa3) {
; #pragma unroll
;   for (int r = 0; r < 16; ++r) p1[r] = __builtin_amdgcn_exp2f(p1[r]);
;   float ps = 0;
; #pragma unroll
;   for (int r = 0; r < 16; ++r) ps += p0[r];
; #pragma unroll
;   for (int r = 0; r < 16; ++r) ps += p1[r];
;   { auto rr = __builtin_amdgcn_permlane32_swap(__float_as_uint(ps), __float_as_uint(ps), false, false);
;     ps = __uint_as_float(rr[0]) + __uint_as_float(rr[1]); }
;   l_reg = l_reg * alpha + ps;
;     ...
;   PK4(p0, 0, pa0); PK4(p0, 8, pa1); PK4(p1, 0, pa2); PK4(p1, 8, pa3);
	v_mfma_f32_32x32x16_bf16 v[66:81], v[234:237], v[238:241], v[66:81]
	v_mfma_f32_32x32x16_bf16 v[82:97], v[230:233], v[238:241], v[82:97]
	ds_read_b128 v[230:233], v197 offset:2048
	s_waitcnt lgkmcnt(0)
	v_mfma_f32_32x32x16_bf16 v[66:81], v[154:157], v[230:233], v[66:81]
	v_add_f32_e32 v154, 0, v226
	v_add_f32_e32 v154, v228, v154
	v_add_f32_e32 v154, v224, v154
	v_add_f32_e32 v154, v227, v154
	v_add_f32_e32 v154, v221, v154
	v_add_f32_e32 v154, v225, v154
	v_add_f32_e32 v154, v220, v154
	v_add_f32_e32 v154, v222, v154
	v_add_f32_e32 v154, v217, v154
	v_add_f32_e32 v154, v219, v154
	v_add_f32_e32 v154, v215, v154
	v_add_f32_e32 v154, v218, v154
	v_add_f32_e32 v154, v213, v154
	v_add_f32_e32 v154, v216, v154
	v_add_f32_e32 v154, v212, v154
	v_add_f32_e32 v154, v214, v154
	v_add_f32_e32 v154, v182, v154
	v_add_f32_e32 v154, v183, v154
	v_add_f32_e32 v154, v180, v154
	v_add_f32_e32 v154, v181, v154
	v_add_f32_e32 v154, v178, v154
	v_add_f32_e32 v154, v179, v154
	v_add_f32_e32 v154, v176, v154
	v_add_f32_e32 v154, v177, v154
	v_add_f32_e32 v154, v168, v154
	v_mfma_f32_32x32x16_bf16 v[82:97], v[158:161], v[230:233], v[82:97]
	v_exp_f32_e32 v230, v165
	v_add_f32_e32 v154, v169, v154
	v_exp_f32_e32 v231, v162
	v_add_f32_e32 v154, v223, v154
	v_exp_f32_e32 v232, v163
	v_add_f32_e32 v154, v167, v154
	v_add_f32_e32 v154, v229, v154
	v_add_f32_e32 v154, v230, v154
	v_add_f32_e32 v154, v231, v154
	v_add_f32_e32 v210, v232, v154
	v_mov_b32_e32 v211, v210
	v_cvt_pk_bf16_f32 v154, v226, v228
	v_cvt_pk_bf16_f32 v155, v224, v227
	v_cvt_pk_bf16_f32 v156, v221, v225
	s_nop 1
	v_permlane32_swap_b32_e32 v210, v211
	v_cvt_pk_bf16_f32 v157, v220, v222
	v_permlane32_swap_b32_e32 v154, v156
	v_cvt_pk_bf16_f32 v158, v217, v219
	v_cvt_pk_bf16_f32 v159, v215, v218
	v_cvt_pk_bf16_f32 v160, v213, v216
	v_cvt_pk_bf16_f32 v161, v212, v214
	v_cvt_pk_bf16_f32 v162, v182, v183
	v_cvt_pk_bf16_f32 v163, v180, v181
	v_cvt_pk_bf16_f32 v164, v178, v179
	v_cvt_pk_bf16_f32 v165, v176, v177
	v_cvt_pk_bf16_f32 v166, v168, v169
	v_cvt_pk_bf16_f32 v167, v223, v167
	v_cvt_pk_bf16_f32 v168, v229, v230
	v_cvt_pk_bf16_f32 v169, v231, v232
	v_permlane32_swap_b32_e32 v155, v157
	v_permlane32_swap_b32_e32 v158, v160
	v_permlane32_swap_b32_e32 v159, v161
	v_permlane32_swap_b32_e32 v162, v164
	v_permlane32_swap_b32_e32 v163, v165
	v_permlane32_swap_b32_e32 v166, v168
	v_permlane32_swap_b32_e32 v167, v169
	s_lshl_b32 s10, s2, 14
	s_add_i32 s9, s10, 0
	v_add_u32_e32 v176, s9, v201
	s_lshl_b32 s6, s2, 13
	s_waitcnt vmcnt(0)
	s_waitcnt vmcnt(4)
	ds_write_b128 v176, v[134:137]
	v_add_u32_e32 v134, s9, v202
	s_add_i32 s9, s9, s6
	s_waitcnt vmcnt(3)
	ds_write_b128 v134, v[138:141]
	v_add_u32_e32 v134, s9, v203
	s_waitcnt vmcnt(2)
	ds_write_b128 v134, v[142:145] offset:49152
	s_waitcnt vmcnt(1)
	ds_write_b128 v134, v[146:149] offset:61440
	v_add_u32_e32 v134, s9, v204
	v_lshl_add_u64 v[176:177], s[94:95], 0, v[174:175]
	s_mov_b32 s6, 0x198c0000
	s_waitcnt vmcnt(0)
	ds_write_b128 v134, v[150:153] offset:49152
	v_add_co_u32_e32 v134, vcc, s6, v176
	s_mov_b32 s6, 0x198e0000
	s_nop 0
	v_addc_co_u32_e32 v135, vcc, 0, v177, vcc
	v_add_co_u32_e32 v138, vcc, s6, v176
	s_mov_b32 s6, 0x150c0000
	s_nop 0
	v_addc_co_u32_e32 v139, vcc, 0, v177, vcc
	v_add_co_u32_e32 v142, vcc, s6, v176
	s_mov_b32 s6, 0x150e0000
	s_nop 0
	v_addc_co_u32_e32 v143, vcc, 0, v177, vcc
	v_add_co_u32_e32 v146, vcc, s6, v176
	v_lshl_add_u64 v[178:179], s[94:95], 0, v[172:173]
	s_nop 0
	v_addc_co_u32_e32 v147, vcc, 0, v177, vcc
	s_mov_b32 s6, 0x9906000
	v_add_co_u32_e32 v150, vcc, s6, v178
	global_load_dwordx4 v[134:137], v[134:135], off
	s_nop 0
	global_load_dwordx4 v[138:141], v[138:139], off
	v_addc_co_u32_e32 v151, vcc, 0, v179, vcc
	global_load_dwordx4 v[142:145], v[142:143], off
	s_nop 0
	global_load_dwordx4 v[146:149], v[146:147], off
	s_nop 0
	global_load_dwordx4 v[150:153], v[150:151], off
	v_lshl_add_u32 v224, s48, 14, v196
	ds_read_b64_tr_b16 v[180:181], v224 offset:0
	ds_read_b64_tr_b16 v[182:183], v224 offset:0x800
	ds_read_b64_tr_b16 v[212:213], v224 offset:0x1000
	ds_read_b64_tr_b16 v[214:215], v224 offset:0x1800
	ds_read_b64_tr_b16 v[216:217], v224 offset:0x2000
	ds_read_b64_tr_b16 v[218:219], v224 offset:0x2800
	ds_read_b64_tr_b16 v[220:221], v224 offset:0x3000
	ds_read_b64_tr_b16 v[222:223], v224 offset:0x3800
	s_waitcnt lgkmcnt(0)
	s_nop 0
	v_mfma_f32_32x32x16_bf16 v[2:17], v[154:157], v[180:183], v[2:17]
	ds_read_b64_tr_b16 v[180:181], v224 offset:0x200
	ds_read_b64_tr_b16 v[182:183], v224 offset:0xa00
	v_mfma_f32_32x32x16_bf16 v[2:17], v[158:161], v[212:215], v[2:17]
	ds_read_b64_tr_b16 v[212:213], v224 offset:0x1200
	ds_read_b64_tr_b16 v[214:215], v224 offset:0x1a00
	v_mfma_f32_32x32x16_bf16 v[2:17], v[162:165], v[216:219], v[2:17]
	ds_read_b64_tr_b16 v[216:217], v224 offset:0x2200
	ds_read_b64_tr_b16 v[218:219], v224 offset:0x2a00
	v_mfma_f32_32x32x16_bf16 v[2:17], v[166:169], v[220:223], v[2:17]
	ds_read_b64_tr_b16 v[220:221], v224 offset:0x3200
	ds_read_b64_tr_b16 v[222:223], v224 offset:0x3a00
	s_waitcnt lgkmcnt(0)
	v_mfma_f32_32x32x16_bf16 v[50:65], v[154:157], v[180:183], v[50:65]
	ds_read_b64_tr_b16 v[180:181], v224 offset:0x400
	ds_read_b64_tr_b16 v[182:183], v224 offset:0xc00
	v_mfma_f32_32x32x16_bf16 v[50:65], v[158:161], v[212:215], v[50:65]
	ds_read_b64_tr_b16 v[212:213], v224 offset:0x1400
	ds_read_b64_tr_b16 v[214:215], v224 offset:0x1c00
	v_mfma_f32_32x32x16_bf16 v[50:65], v[162:165], v[216:219], v[50:65]
	ds_read_b64_tr_b16 v[216:217], v224 offset:0x2400
	ds_read_b64_tr_b16 v[218:219], v224 offset:0x2c00
	v_mfma_f32_32x32x16_bf16 v[50:65], v[166:169], v[220:223], v[50:65]
	ds_read_b64_tr_b16 v[220:221], v224 offset:0x3400
	ds_read_b64_tr_b16 v[222:223], v224 offset:0x3c00
	s_waitcnt lgkmcnt(0)
; template <int DQK> __device__ __forceinline__ void partialSM(f32x16& p0, f32x16& p1, float& m_reg, float& mn, float& alpha) {
;   constexpr float SCALE = Sc<DQK>::SCALE; constexpr float C = SCALE * 1.4426950408889634f;
;   float pmax = p0[0];
; #pragma unroll
;   for (int r = 1; r < 16; ++r) pmax = fmaxf(pmax, p0[r]);
; #pragma unroll
;   for (int r = 0; r < 16; ++r) pmax = fmaxf(pmax, p1[r]);
;   { auto rr = __builtin_amdgcn_permlane32_swap(__float_as_uint(pmax), __float_as_uint(pmax), false, false);
;     pmax = fmaxf(__uint_as_float(rr[0]), __uint_as_float(rr[1])); }
;   if (__builtin_expect(__all(pmax - m_reg <= THR / SCALE), 1)) { mn = m_reg; alpha = 1.f; }
;   else { mn = fmaxf(m_reg, pmax); alpha = __builtin_amdgcn_exp2f((m_reg - mn) * C); m_reg = mn; }
;   float mnC = -mn * C;
; #pragma unroll
;   for (int r = 0; r < 16; ++r) p0[r] = fmaf(p0[r], C, mnC);
; #pragma unroll
;   for (int r = 0; r < 16; ++r) p1[r] = fmaf(p1[r], C, mnC);
; #pragma unroll
;   for (int r = 0; r < 16; ++r) p0[r] = __builtin_amdgcn_exp2f(p0[r]);
	v_mfma_f32_32x32x16_bf16 v[34:49], v[154:157], v[180:183], v[34:49]
	ds_read_b64_tr_b16 v[180:181], v224 offset:0x600
	ds_read_b64_tr_b16 v[182:183], v224 offset:0xe00
	v_mfma_f32_32x32x16_bf16 v[34:49], v[158:161], v[212:215], v[34:49]
	ds_read_b64_tr_b16 v[212:213], v224 offset:0x1600
	ds_read_b64_tr_b16 v[214:215], v224 offset:0x1e00
	v_mfma_f32_32x32x16_bf16 v[34:49], v[162:165], v[216:219], v[34:49]
	ds_read_b64_tr_b16 v[216:217], v224 offset:0x2600
	ds_read_b64_tr_b16 v[218:219], v224 offset:0x2e00
	v_mfma_f32_32x32x16_bf16 v[34:49], v[166:169], v[220:223], v[34:49]
	ds_read_b64_tr_b16 v[220:221], v224 offset:0x3600
	ds_read_b64_tr_b16 v[222:223], v224 offset:0x3e00
	s_waitcnt lgkmcnt(0)
	v_mfma_f32_32x32x16_bf16 v[18:33], v[154:157], v[180:183], v[18:33]
	v_max_f32_e32 v154, v83, v83
	v_max_f32_e32 v155, v82, v82
	v_max_f32_e32 v154, v155, v154
	v_max3_f32 v154, v154, v84, v85
	v_max3_f32 v154, v154, v86, v87
	v_max3_f32 v154, v154, v88, v89
	v_max3_f32 v154, v154, v90, v91
	v_max3_f32 v154, v154, v92, v93
	v_max3_f32 v154, v154, v94, v95
	v_mfma_f32_32x32x16_bf16 v[18:33], v[158:161], v[212:215], v[18:33]
	v_max3_f32 v154, v154, v96, v97
	v_max3_f32 v154, v154, v66, v67
	v_max3_f32 v154, v154, v68, v69
	v_max3_f32 v154, v154, v70, v71
	v_max3_f32 v154, v154, v72, v73
	v_max3_f32 v154, v154, v74, v75
	v_max3_f32 v154, v154, v76, v77
	v_max3_f32 v154, v154, v78, v79
	v_mfma_f32_32x32x16_bf16 v[18:33], v[162:165], v[216:219], v[18:33]
	v_max3_f32 v154, v154, v80, v81
	v_mov_b32_e32 v155, v154
	s_nop 1
	v_permlane32_swap_b32_e32 v154, v155
	v_max_f32_e32 v155, v155, v155
	v_max_f32_e32 v154, v154, v154
	v_max_f32_e32 v154, v154, v155
	v_sub_f32_e32 v155, v154, v209
	v_cmp_ge_f32_e32 vcc, s49, v155
	v_max_f32_e32 v155, v209, v209
	v_max_f32_e32 v154, v155, v154
	v_mfma_f32_32x32x16_bf16 v[18:33], v[166:169], v[220:223], v[18:33]
	v_sub_f32_e32 v155, v209, v154
	v_mul_f32_e32 v155, 0x3dd53b94, v155
	v_exp_f32_e32 v155, v155
	s_cmp_eq_u64 vcc, exec
	s_cselect_b64 s[40:41], -1, 0
	s_waitcnt lgkmcnt(0)
	s_barrier
	v_cndmask_b32_e64 v223, v155, 1.0, s[40:41]
	v_cmp_gt_f32_e32 vcc, 1.0, v223
	s_cbranch_vccz .LBB0_55
	s_and_saveexec_b64 s[6:7], s[38:39]
	ds_write_b32 v198, v223 offset:128
	s_or_b64 exec, exec, s[6:7]
	s_waitcnt lgkmcnt(0)
	v_add_u32_e32 v155, v195, v170
	ds_read_b128 v[156:159], v155 offset:224
	ds_read_b128 v[160:163], v155 offset:192
	ds_read_b128 v[164:167], v155 offset:160
	ds_read_b128 v[180:183], v155 offset:128
	s_waitcnt lgkmcnt(3)
	v_pk_mul_f32 v[14:15], v[14:15], v[156:157]
	s_waitcnt lgkmcnt(2)
	v_pk_mul_f32 v[10:11], v[10:11], v[160:161]
	s_waitcnt lgkmcnt(1)
	v_pk_mul_f32 v[6:7], v[6:7], v[164:165]
	v_pk_mul_f32 v[16:17], v[16:17], v[158:159]
	v_pk_mul_f32 v[12:13], v[12:13], v[162:163]
	v_pk_mul_f32 v[8:9], v[8:9], v[166:167]
	s_waitcnt lgkmcnt(0)
	v_pk_mul_f32 v[4:5], v[4:5], v[182:183]
	v_pk_mul_f32 v[2:3], v[2:3], v[180:181]
	v_pk_mul_f32 v[62:63], v[62:63], v[156:157]
	v_pk_mul_f32 v[58:59], v[58:59], v[160:161]
	v_pk_mul_f32 v[54:55], v[54:55], v[164:165]
	v_pk_mul_f32 v[64:65], v[64:65], v[158:159]
	v_pk_mul_f32 v[60:61], v[60:61], v[162:163]
	v_pk_mul_f32 v[56:57], v[56:57], v[166:167]
	v_pk_mul_f32 v[52:53], v[52:53], v[182:183]
	v_pk_mul_f32 v[50:51], v[50:51], v[180:181]
	v_pk_mul_f32 v[46:47], v[46:47], v[156:157]
	v_pk_mul_f32 v[42:43], v[42:43], v[160:161]
	v_pk_mul_f32 v[38:39], v[38:39], v[164:165]
	v_pk_mul_f32 v[48:49], v[48:49], v[158:159]
	v_pk_mul_f32 v[44:45], v[44:45], v[162:163]
	v_pk_mul_f32 v[40:41], v[40:41], v[166:167]
	v_pk_mul_f32 v[36:37], v[36:37], v[182:183]
	v_pk_mul_f32 v[34:35], v[34:35], v[180:181]
	v_pk_mul_f32 v[30:31], v[30:31], v[156:157]
	v_pk_mul_f32 v[26:27], v[26:27], v[160:161]
	v_pk_mul_f32 v[22:23], v[22:23], v[164:165]
	v_pk_mul_f32 v[32:33], v[32:33], v[158:159]
	v_pk_mul_f32 v[28:29], v[28:29], v[162:163]
	v_pk_mul_f32 v[24:25], v[24:25], v[166:167]
	v_pk_mul_f32 v[20:21], v[20:21], v[182:183]
	v_pk_mul_f32 v[18:19], v[18:19], v[180:181]
.LBB0_55:
	v_cndmask_b32_e64 v180, v154, v209, s[40:41]
	v_mul_f32_e32 v213, 0xbdd53b94, v180
	v_fmamk_f32 v82, v82, 0x3dd53b94, v213
	v_fmamk_f32 v83, v83, 0x3dd53b94, v213
	v_fmamk_f32 v84, v84, 0x3dd53b94, v213
	v_fmamk_f32 v90, v90, 0x3dd53b94, v213
	v_fmamk_f32 v91, v91, 0x3dd53b94, v213
	v_fmamk_f32 v92, v92, 0x3dd53b94, v213
	v_fmamk_f32 v93, v93, 0x3dd53b94, v213
	v_fmamk_f32 v94, v94, 0x3dd53b94, v213
	v_exp_f32_e32 v165, v82
	v_exp_f32_e32 v168, v83
	v_exp_f32_e32 v169, v84
	v_exp_f32_e32 v162, v90
	v_exp_f32_e32 v163, v91
	v_exp_f32_e32 v164, v92
	v_exp_f32_e32 v166, v93
	v_exp_f32_e32 v167, v94
	s_add_i32 s6, s2, 1
	s_cmp_lg_u32 s2, 2
	v_fmamk_f32 v85, v85, 0x3dd53b94, v213
	v_fmamk_f32 v86, v86, 0x3dd53b94, v213
	v_fmamk_f32 v87, v87, 0x3dd53b94, v213
	v_fmamk_f32 v88, v88, 0x3dd53b94, v213
	v_fmamk_f32 v89, v89, 0x3dd53b94, v213
	v_fmamk_f32 v95, v95, 0x3dd53b94, v213
	v_fmamk_f32 v96, v96, 0x3dd53b94, v213
	v_fmamk_f32 v97, v97, 0x3dd53b94, v213
	v_fmamk_f32 v229, v77, 0x3dd53b94, v213
	v_fmamk_f32 v230, v78, 0x3dd53b94, v213
	s_cselect_b32 s12, s6, 0
	v_fmamk_f32 v217, v66, 0x3dd53b94, v213
	v_fmamk_f32 v218, v67, 0x3dd53b94, v213
	v_fmamk_f32 v219, v68, 0x3dd53b94, v213
	v_fmamk_f32 v220, v69, 0x3dd53b94, v213
	v_fmamk_f32 v221, v70, 0x3dd53b94, v213
	v_fmamk_f32 v222, v71, 0x3dd53b94, v213
	v_fmamk_f32 v224, v72, 0x3dd53b94, v213
	v_fmamk_f32 v225, v73, 0x3dd53b94, v213
	v_fmamk_f32 v226, v74, 0x3dd53b94, v213
	v_fmamk_f32 v227, v75, 0x3dd53b94, v213
	v_fmamk_f32 v228, v76, 0x3dd53b94, v213
	v_fmamk_f32 v231, v79, 0x3dd53b94, v213
	v_fmamk_f32 v232, v80, 0x3dd53b94, v213
	v_fmac_f32_e32 v213, 0x3dd53b94, v81
	v_exp_f32_e32 v183, v85
	v_exp_f32_e32 v209, v86
	v_exp_f32_e32 v214, v87
	v_exp_f32_e32 v215, v88
	v_exp_f32_e32 v216, v89
	v_exp_f32_e32 v181, v95
	v_exp_f32_e32 v182, v96
	v_exp_f32_e32 v212, v97
	v_add_u32_e32 v233, s9, v207
	v_add_u32_e32 v242, s9, v200
	ds_read_b128 v[154:157], v233 offset:49152
	ds_read_b128 v[158:161], v233 offset:61440
	ds_read_b128 v[66:69], v242 offset:61440
	ds_read_b128 v[70:73], v242 offset:49152
	v_add_u32_e32 v243, s9, v205
	v_add_u32_e32 v246, s9, v206
	s_waitcnt lgkmcnt(0)
; template <int DQK, int KW, int QSP> __device__ __forceinline__ void qkt(f32x16& p0, f32x16& p1, const char* Ks, const int (&kb)[4], const bf16x8* qr, const char* qsp, const f32x16& cinit) {
;   p0 = cinit; p1 = cinit;
;   constexpr int N = DQK / 16;
;     ...
;   bf16x8 f0[2], f1[2];
;   f0[0] = KRD(0, 1); f1[0] = KRD(0, 0);
; #pragma unroll
;   for (int d0 = 0; d0 < N; ++d0) {
;     if (d0 + 1 < N) { f0[(d0 + 1) & 1] = KRD(d0 + 1, 1); f1[(d0 + 1) & 1] = KRD(d0 + 1, 0); }
;     __builtin_amdgcn_sched_barrier(0x406);
;     bf16x8 qf;
;     if constexpr (QSP > 0) { if (d0 >= N - QSP) qf = *reinterpret_cast<const bf16x8*>(qsp + (d0 - (N - QSP)) * 1024); else qf = qr[d0]; } else qf = qr[d0];
;     p0 = __builtin_amdgcn_mfma_f32_32x32x16_bf16(f0[d0 & 1], qf, p0, 0, 0, 0);
;     p1 = __builtin_amdgcn_mfma_f32_32x32x16_bf16(f1[d0 & 1], qf, p1, 0, 0, 0);
;     __builtin_amdgcn_sched_barrier(0x406); }
	v_mfma_f32_32x32x16_bf16 v[82:97], v[70:73], v[130:133], 0
	v_exp_f32_e32 v217, v217
	v_exp_f32_e32 v218, v218
	v_exp_f32_e32 v219, v219
	v_exp_f32_e32 v220, v220
	v_exp_f32_e32 v221, v221
	v_exp_f32_e32 v222, v222
	v_exp_f32_e32 v224, v224
	v_mfma_f32_32x32x16_bf16 v[66:81], v[66:69], v[130:133], 0
	ds_read_b128 v[234:237], v243 offset:49152
	ds_read_b128 v[238:241], v243 offset:61440
	v_exp_f32_e32 v225, v225
	v_exp_f32_e32 v226, v226
	v_exp_f32_e32 v227, v227
	v_exp_f32_e32 v228, v228
	v_exp_f32_e32 v231, v231
	v_exp_f32_e32 v232, v232
	v_mfma_f32_32x32x16_bf16 v[66:81], v[158:161], v[126:129], v[66:81]
	v_exp_f32_e32 v213, v213
	v_mfma_f32_32x32x16_bf16 v[82:97], v[154:157], v[126:129], v[82:97]
	ds_read_b128 v[154:157], v246 offset:49152
	ds_read_b128 v[158:161], v246 offset:61440
	s_waitcnt lgkmcnt(2)
	v_mfma_f32_32x32x16_bf16 v[66:81], v[238:241], v[122:125], v[66:81]
	v_mfma_f32_32x32x16_bf16 v[82:97], v[234:237], v[122:125], v[82:97]
	ds_read_b128 v[234:237], v242 offset:49280
	ds_read_b128 v[238:241], v242 offset:61568
	s_waitcnt lgkmcnt(2)
	v_mfma_f32_32x32x16_bf16 v[66:81], v[158:161], v[118:121], v[66:81]
	v_mfma_f32_32x32x16_bf16 v[82:97], v[154:157], v[118:121], v[82:97]
	ds_read_b128 v[154:157], v233 offset:49280
	ds_read_b128 v[158:161], v233 offset:61568
	s_waitcnt lgkmcnt(2)
	v_mfma_f32_32x32x16_bf16 v[66:81], v[238:241], v[114:117], v[66:81]
	v_mfma_f32_32x32x16_bf16 v[82:97], v[234:237], v[114:117], v[82:97]
	ds_read_b128 v[234:237], v243 offset:49280
	ds_read_b128 v[238:241], v243 offset:61568
	s_waitcnt lgkmcnt(2)
	v_mfma_f32_32x32x16_bf16 v[66:81], v[158:161], v[110:113], v[66:81]
	v_mfma_f32_32x32x16_bf16 v[82:97], v[154:157], v[110:113], v[82:97]
	ds_read_b128 v[154:157], v246 offset:49280
	ds_read_b128 v[158:161], v246 offset:61568
	s_waitcnt lgkmcnt(2)
	v_mfma_f32_32x32x16_bf16 v[66:81], v[238:241], v[106:109], v[66:81]
	v_mfma_f32_32x32x16_bf16 v[82:97], v[234:237], v[106:109], v[82:97]
	ds_read_b128 v[234:237], v242 offset:49408
	ds_read_b128 v[238:241], v242 offset:61696
	s_waitcnt lgkmcnt(2)
	v_mfma_f32_32x32x16_bf16 v[66:81], v[158:161], v[102:105], v[66:81]
	v_mfma_f32_32x32x16_bf16 v[82:97], v[154:157], v[102:105], v[82:97]
	ds_read_b128 v[154:157], v233 offset:49408
	ds_read_b128 v[158:161], v233 offset:61696
	v_exp_f32_e32 v233, v229
	s_waitcnt lgkmcnt(2)
	v_mfma_f32_32x32x16_bf16 v[66:81], v[238:241], v[98:101], v[66:81]
	v_mfma_f32_32x32x16_bf16 v[82:97], v[234:237], v[98:101], v[82:97]
	ds_read_b128 v[234:237], v243 offset:49408
	ds_read_b128 v[238:241], v243 offset:61696
	s_waitcnt lgkmcnt(2)
	v_mfma_f32_32x32x16_bf16 v[66:81], v[158:161], v[248:251], v[66:81]
	v_mfma_f32_32x32x16_bf16 v[82:97], v[154:157], v[248:251], v[82:97]
	ds_read_b128 v[158:161], v246 offset:49408
	ds_read_b128 v[154:157], v246 offset:61696
	ds_read_b128 v[242:245], v197 offset:1024
	s_waitcnt lgkmcnt(0)
	v_mfma_f32_32x32x16_bf16 v[66:81], v[238:241], v[242:245], v[66:81]
	v_mfma_f32_32x32x16_bf16 v[82:97], v[234:237], v[242:245], v[82:97]
	ds_read_b128 v[234:237], v197 offset:2048
	s_waitcnt lgkmcnt(0)
	v_mfma_f32_32x32x16_bf16 v[66:81], v[154:157], v[234:237], v[66:81]
	v_add_f32_e32 v154, 0, v165
	v_add_f32_e32 v154, v168, v154
	v_add_f32_e32 v154, v169, v154
	v_add_f32_e32 v154, v183, v154
	v_add_f32_e32 v154, v209, v154
	v_add_f32_e32 v154, v214, v154
	v_add_f32_e32 v154, v215, v154
	v_add_f32_e32 v154, v216, v154
	v_add_f32_e32 v154, v162, v154
	v_add_f32_e32 v154, v163, v154
	v_add_f32_e32 v154, v164, v154
	v_add_f32_e32 v154, v166, v154
	v_add_f32_e32 v154, v167, v154
	v_add_f32_e32 v154, v181, v154
	v_add_f32_e32 v154, v182, v154
	v_add_f32_e32 v154, v212, v154
	v_add_f32_e32 v154, v217, v154
	v_add_f32_e32 v154, v218, v154
	v_add_f32_e32 v154, v219, v154
	v_add_f32_e32 v154, v220, v154
	v_add_f32_e32 v154, v221, v154
	v_add_f32_e32 v154, v222, v154
	v_add_f32_e32 v154, v224, v154
	v_add_f32_e32 v154, v225, v154
	v_mfma_f32_32x32x16_bf16 v[82:97], v[158:161], v[234:237], v[82:97]
	v_exp_f32_e32 v234, v230
	v_add_f32_e32 v154, v226, v154
	v_add_f32_e32 v154, v227, v154
	v_add_f32_e32 v154, v228, v154
	v_add_f32_e32 v154, v233, v154
	v_add_f32_e32 v154, v234, v154
	v_add_f32_e32 v154, v231, v154
	v_add_f32_e32 v154, v232, v154
	v_add_f32_e32 v229, v213, v154
	v_mov_b32_e32 v230, v229
	v_cvt_pk_bf16_f32 v154, v165, v168
	v_cvt_pk_bf16_f32 v155, v169, v183
	v_cvt_pk_bf16_f32 v156, v209, v214
	v_cvt_pk_bf16_f32 v157, v215, v216
	v_cvt_pk_bf16_f32 v158, v162, v163
	v_cvt_pk_bf16_f32 v159, v164, v166
	v_cvt_pk_bf16_f32 v160, v167, v181
	v_cvt_pk_bf16_f32 v161, v182, v212
	v_cvt_pk_bf16_f32 v162, v217, v218
	v_cvt_pk_bf16_f32 v163, v219, v220
	v_cvt_pk_bf16_f32 v164, v221, v222
	v_cvt_pk_bf16_f32 v165, v224, v225
	v_cvt_pk_bf16_f32 v166, v226, v227
	v_cvt_pk_bf16_f32 v167, v228, v233
	v_cvt_pk_bf16_f32 v168, v234, v231
	v_cvt_pk_bf16_f32 v169, v232, v213
	s_nop 1
	v_permlane32_swap_b32_e32 v229, v230
	v_permlane32_swap_b32_e32 v154, v156
	v_permlane32_swap_b32_e32 v155, v157
	v_permlane32_swap_b32_e32 v158, v160
	v_permlane32_swap_b32_e32 v159, v161
	v_permlane32_swap_b32_e32 v162, v164
	v_permlane32_swap_b32_e32 v163, v165
	v_permlane32_swap_b32_e32 v166, v168
	v_permlane32_swap_b32_e32 v167, v169
	s_lshl_b32 s11, s12, 14
	s_add_i32 s13, s11, 0
	v_add_u32_e32 v181, s13, v201
	s_lshl_b32 s6, s12, 13
	s_waitcnt vmcnt(0)
	s_waitcnt vmcnt(4)
	ds_write_b128 v181, v[134:137]
	v_add_u32_e32 v181, s13, v202
	s_add_i32 s13, s13, s6
	s_cmp_ge_u32 s31, s33
	s_waitcnt vmcnt(3)
	ds_write_b128 v181, v[138:141]
	v_add_u32_e32 v181, s13, v203
	s_cselect_b64 s[6:7], -1, 0
	s_waitcnt vmcnt(2)
	ds_write_b128 v181, v[142:145] offset:49152
	s_waitcnt vmcnt(1)
	ds_write_b128 v181, v[146:149] offset:61440
	v_add_u32_e32 v181, s13, v204
	s_and_b64 vcc, exec, s[6:7]
	s_waitcnt vmcnt(0)
	ds_write_b128 v181, v[150:153] offset:49152
	s_cbranch_vccnz .LBB0_57
	v_add_co_u32_e32 v134, vcc, 0x19900000, v176
	s_nop 1
	v_addc_co_u32_e32 v135, vcc, 0, v177, vcc
	v_add_co_u32_e32 v138, vcc, 0x19920000, v176
	s_nop 1
	v_addc_co_u32_e32 v139, vcc, 0, v177, vcc
	v_add_co_u32_e32 v142, vcc, 0x15100000, v176
	global_load_dwordx4 v[134:137], v[134:135], off
	s_nop 0
	global_load_dwordx4 v[138:141], v[138:139], off
	v_addc_co_u32_e32 v143, vcc, 0, v177, vcc
	v_add_co_u32_e32 v146, vcc, 0x15120000, v176
	s_nop 1
	v_addc_co_u32_e32 v147, vcc, 0, v177, vcc
	v_add_co_u32_e32 v150, vcc, 0x9908000, v178
	global_load_dwordx4 v[142:145], v[142:143], off
	s_nop 0
	global_load_dwordx4 v[146:149], v[146:147], off
	v_addc_co_u32_e32 v151, vcc, 0, v179, vcc
	global_load_dwordx4 v[150:153], v[150:151], off
